# ctx units on RG workgroups + static prio raise for waves 4-7 in the attention tile loop
# baseline (speedup 1.0000x reference)
.LBB0_692:
	s_and_b64 vcc, exec, s[4:5]
	s_cbranch_vccz .LBB0_783
	s_and_b32 s0, s22, 0x7fffffc0
	s_cmpk_lg_i32 s0, 0x100
	s_mov_b64 s[4:5], -1
	s_cbranch_scc0 .LBB0_745
	s_cmpk_lt_u32 s22, 0x200
	s_cbranch_scc1 .LBB0_744
	s_add_i32 s0, s22, 0xfffffe00
	v_mbcnt_lo_u32_b32 v0, -1, 0
	v_mbcnt_hi_u32_b32 v0, -1, v0
	s_lshr_b32 s4, s0, 5
	v_add_u32_e32 v36, s93, v0
	s_lshl_b32 s0, s22, 8
	s_lshl_b32 s12, s4, 11
	v_readfirstlane_b32 s2, v36
	s_and_b32 s0, s0, 0x700
	s_ashr_i32 s5, s2, 6
	s_or_b32 s0, s12, s0
	s_lshl_b32 s2, s5, 5
	v_readlane_b32 s8, v255, 11
	v_and_b32_e32 v0, 31, v36
	s_add_i32 s0, s2, s0
	v_readlane_b32 s9, v255, 12
	s_bfe_u32 s1, s22, 0x20003
	v_or_b32_e32 v4, s0, v0
	v_mov_b64_e32 v[2:3], s[8:9]
	v_bfe_u32 v37, v36, 5, 1
	v_mad_i64_i32 v[2:3], s[2:3], v4, s72, v[2:3]
	s_lshl_b32 s36, s1, 8
	v_lshl_add_u64 v[2:3], v[2:3], 0, s[36:37]
	v_lshlrev_b32_e32 v34, 4, v37
	v_mov_b32_e32 v35, v1
	v_lshl_add_u64 v[30:31], v[2:3], 0, v[34:35]
	global_load_dwordx4 v[2:5], v[30:31], off offset:2560
	global_load_dwordx4 v[6:9], v[30:31], off offset:2592
	global_load_dwordx4 v[10:13], v[30:31], off offset:2624
	global_load_dwordx4 v[14:17], v[30:31], off offset:2656
	global_load_dwordx4 v[18:21], v[30:31], off offset:2688
	global_load_dwordx4 v[22:25], v[30:31], off offset:2720
	global_load_dwordx4 v[26:29], v[30:31], off offset:2752
	s_nop 0
	global_load_dwordx4 v[30:33], v[30:31], off offset:2784
	v_lshlrev_b32_e32 v35, 4, v36
	v_and_b32_e32 v42, 0xf0, v35
	s_movk_i32 s6, 0x60
	v_bitop3_b32 v215, v34, v42, s6 bitop3:0x36
	s_movk_i32 s6, 0x80
	v_bitop3_b32 v216, v34, v42, s6 bitop3:0x36
	s_movk_i32 s6, 0xa0
	v_bitop3_b32 v217, v34, v42, s6 bitop3:0x36
	s_movk_i32 s6, 0xc0
	s_lshl_b32 s2, s5, 9
	s_lshl_b32 s3, s5, 13
	v_bitop3_b32 v218, v34, v42, s6 bitop3:0x36
	s_movk_i32 s6, 0xe0
	s_lshl_b32 s13, s4, 8
	v_bfe_u32 v38, v36, 4, 2
	v_bfe_u32 v39, v36, 2, 3
	v_bitop3_b32 v219, v34, v42, s6 bitop3:0x36
	s_lshl_b32 s6, s5, 3
	s_add_i32 s15, s3, 0
	s_add_i32 s14, s2, 0
	s_lshl_b32 s1, s1, 7
	s_add_i32 s13, s13, 0x8000
	v_lshlrev_b32_e32 v41, 3, v36
	v_or_b32_e32 v43, s6, v38
	v_or_b32_e32 v39, s6, v39
	s_add_i32 s15, s15, 0x11000
	s_add_i32 s14, s14, 0x10000
	s_movk_i32 s2, 0xb00
	v_and_b32_e32 v40, 32, v36
	v_lshlrev_b32_e32 v212, 8, v0
	v_bitop3_b32 v0, v37, v36, 15 bitop3:0x78
	v_and_b32_e32 v37, 24, v41
	v_bitop3_b32 v38, s6, v36, v38 bitop3:0x36
	v_mul_lo_u32 v39, v39, s2
	v_mul_lo_u32 v44, v43, s2
	v_bitop3_b32 v43, v43, v36, 4 bitop3:0x36
	s_add_u32 s36, s8, s36
	v_lshlrev_b32_e32 v38, 3, v38
	v_or3_b32 v37, v40, v37, v39
	s_movk_i32 s2, 0x78
	v_lshlrev_b32_e32 v39, 3, v43
	s_addc_u32 s38, s9, 0
	s_mul_i32 s4, s4, 0xb00000
	v_and_or_b32 v38, v38, s2, v44
	v_lshlrev_b32_e32 v196, 1, v37
	v_and_or_b32 v37, v39, s2, v44
	s_mul_hi_u32 s3, s12, 0x1600
	s_add_u32 s2, s36, s4
	v_add_u32_e32 v45, s15, v212
	s_addc_u32 s3, s38, s3
	s_lshl_b32 s6, s5, 11
	v_bitop3_b32 v213, v34, v42, 32 bitop3:0x36
	v_bitop3_b32 v214, v34, v42, 64 bitop3:0x36
	v_lshl_add_u32 v40, v0, 4, v45
	v_lshlrev_b32_e32 v0, 1, v38
	s_add_u32 s4, s2, 0x1200
	v_add_u32_e32 v43, v45, v213
	v_add_u32_e32 v46, v45, v214
	v_add_u32_e32 v47, v45, v215
	v_add_u32_e32 v48, v45, v216
	v_add_u32_e32 v49, v45, v217
	v_add_u32_e32 v50, v45, v218
	v_add_u32_e32 v45, v45, v219
	s_waitcnt vmcnt(7)
	ds_write_b128 v40, v[2:5]
	s_waitcnt vmcnt(6)
	ds_write_b128 v43, v[6:9]
	s_waitcnt vmcnt(5)
	ds_write_b128 v46, v[10:13]
	s_waitcnt vmcnt(4)
	ds_write_b128 v47, v[14:17]
	s_waitcnt vmcnt(3)
	ds_write_b128 v48, v[18:21]
	s_waitcnt vmcnt(2)
	ds_write_b128 v49, v[22:25]
	s_waitcnt vmcnt(1)
	ds_write_b128 v50, v[26:29]
	s_waitcnt vmcnt(0)
	ds_write_b128 v45, v[30:33]
	s_addc_u32 s5, s3, 0
	v_lshl_add_u64 v[2:3], s[2:3], 0, v[0:1]
	s_add_i32 s39, s6, 0
	v_lshl_add_u32 v198, v37, 1, v249
	v_lshl_add_u64 v[2:3], v[2:3], 0, s[26:27]
	s_add_i32 m0, s39, 0x8000
	v_mov_b32_e32 v199, v1
	global_load_lds_dwordx4 v[2:3], off
	s_mov_b32 m0, s39
	v_lshl_add_u64 v[2:3], s[2:3], 0, v[198:199]
	global_load_lds_dwordx4 v196, s[4:5]
	v_lshl_add_u64 v[2:3], v[2:3], 0, s[26:27]
	s_add_i32 m0, s39, 0x8400
	v_or_b32_e32 v200, 0x80, v196
	global_load_lds_dwordx4 v[2:3], off
	s_add_i32 m0, s39, 0x400
	v_or_b32_e32 v2, 32, v34
	global_load_lds_dwordx4 v200, s[4:5]
	v_lshlrev_b32_e32 v9, 1, v36
	v_and_b32_e32 v11, 0x118, v41
	v_or_b32_e32 v3, 64, v34
	v_or_b32_e32 v4, 0x60, v34
	v_or_b32_e32 v5, 0x80, v34
	v_or_b32_e32 v6, 0xa0, v34
	v_or_b32_e32 v7, 0xc0, v34
	v_or_b32_e32 v8, 0xe0, v34
	v_and_b32_e32 v10, 0xc0, v35
	s_waitcnt vmcnt(0)
	s_movk_i32 s2, 0xf0
	v_bitop3_b32 v222, v2, v212, v42 bitop3:0xde
	v_and_or_b32 v2, v9, 32, v11
	v_mov_b32_e32 v16, v1
	v_mov_b32_e32 v17, v1
	v_bitop3_b32 v220, v34, v35, s2 bitop3:0x78
	v_bitop3_b32 v221, v34, v212, v42 bitop3:0xde
	v_bitop3_b32 v223, v3, v212, v42 bitop3:0xde
	v_bitop3_b32 v224, v4, v212, v42 bitop3:0xde
	v_bitop3_b32 v225, v5, v212, v42 bitop3:0xde
	v_bitop3_b32 v226, v6, v212, v42 bitop3:0xde
	v_bitop3_b32 v227, v7, v212, v42 bitop3:0xde
	v_bitop3_b32 v228, v8, v212, v42 bitop3:0xde
	v_add3_u32 v229, v10, 0, v2
	v_mov_b32_e32 v2, v1
	v_mov_b32_e32 v3, v1
	v_mov_b32_e32 v4, v1
	v_mov_b32_e32 v5, v1
	v_mov_b32_e32 v6, v1
	v_mov_b32_e32 v7, v1
	v_mov_b32_e32 v8, v1
	v_mov_b32_e32 v9, v1
	v_mov_b32_e32 v10, v1
	v_mov_b32_e32 v11, v1
	v_mov_b32_e32 v12, v1
	v_mov_b32_e32 v13, v1
	v_mov_b32_e32 v14, v1
	v_mov_b32_e32 v15, v1
	v_mov_b64_e32 v[80:81], v[16:17]
	v_mov_b64_e32 v[48:49], v[16:17]
	v_mov_b64_e32 v[32:33], v[16:17]
	v_mov_b64_e32 v[128:129], v[16:17]
	v_mov_b64_e32 v[112:113], v[16:17]
	v_mov_b64_e32 v[96:97], v[16:17]
	v_mov_b64_e32 v[64:65], v[16:17]
	v_mov_b32_e32 v197, v1
	v_mov_b32_e32 v201, v1
	s_mov_b32 s40, 0
	v_mov_b32_e32 v202, v1
	v_mov_b32_e32 v203, v1
	v_mov_b32_e32 v231, 0
	s_mov_b64 s[4:5], 0
	s_mov_b64 s[6:7], -1
	v_mov_b64_e32 v[78:79], v[14:15]
	v_mov_b64_e32 v[76:77], v[12:13]
	v_mov_b64_e32 v[74:75], v[10:11]
	v_mov_b64_e32 v[72:73], v[8:9]
	v_mov_b64_e32 v[70:71], v[6:7]
	v_mov_b64_e32 v[68:69], v[4:5]
	v_mov_b64_e32 v[66:67], v[2:3]
	v_mov_b64_e32 v[46:47], v[14:15]
	v_mov_b64_e32 v[44:45], v[12:13]
	v_mov_b64_e32 v[42:43], v[10:11]
	v_mov_b64_e32 v[40:41], v[8:9]
	v_mov_b64_e32 v[38:39], v[6:7]
	v_mov_b64_e32 v[36:37], v[4:5]
	v_mov_b64_e32 v[34:35], v[2:3]
	v_mov_b64_e32 v[30:31], v[14:15]
	v_mov_b64_e32 v[28:29], v[12:13]
	v_mov_b64_e32 v[26:27], v[10:11]
	v_mov_b64_e32 v[24:25], v[8:9]
	v_mov_b64_e32 v[22:23], v[6:7]
	v_mov_b64_e32 v[20:21], v[4:5]
	v_mov_b64_e32 v[18:19], v[2:3]
	v_mov_b64_e32 v[126:127], v[14:15]
	v_mov_b64_e32 v[124:125], v[12:13]
	v_mov_b64_e32 v[122:123], v[10:11]
	v_mov_b64_e32 v[120:121], v[8:9]
	v_mov_b64_e32 v[118:119], v[6:7]
	v_mov_b64_e32 v[116:117], v[4:5]
	v_mov_b64_e32 v[114:115], v[2:3]
	v_mov_b64_e32 v[110:111], v[14:15]
	v_mov_b64_e32 v[108:109], v[12:13]
	v_mov_b64_e32 v[106:107], v[10:11]
	v_mov_b64_e32 v[104:105], v[8:9]
	v_mov_b64_e32 v[102:103], v[6:7]
	v_mov_b64_e32 v[100:101], v[4:5]
	v_mov_b64_e32 v[98:99], v[2:3]
	v_mov_b64_e32 v[94:95], v[14:15]
	v_mov_b64_e32 v[92:93], v[12:13]
	v_mov_b64_e32 v[90:91], v[10:11]
	v_mov_b64_e32 v[88:89], v[8:9]
	v_mov_b64_e32 v[86:87], v[6:7]
	v_mov_b64_e32 v[84:85], v[4:5]
	v_mov_b64_e32 v[82:83], v[2:3]
	v_mov_b64_e32 v[62:63], v[14:15]
	v_mov_b64_e32 v[60:61], v[12:13]
	v_mov_b64_e32 v[58:59], v[10:11]
	v_mov_b64_e32 v[56:57], v[8:9]
	v_mov_b64_e32 v[54:55], v[6:7]
	v_mov_b64_e32 v[52:53], v[4:5]
	v_mov_b64_e32 v[50:51], v[2:3]
	v_mov_b32_e32 v230, 0
	s_waitcnt vmcnt(0) lgkmcnt(0)
	s_barrier
	s_cmp_lt_u32 s61, 4
	s_cbranch_scc1 .Lattn_prio0
	s_setprio 1
.Lattn_prio0:
	s_branch .LBB0_699
.LBB0_696:
	s_or_b64 exec, exec, s[4:5]
	v_ashrrev_i32_e32 v130, 3, v130
	v_lshlrev_b32_e32 v130, 2, v130
	v_and_b32_e32 v130, -16, v130
	s_waitcnt lgkmcnt(0)
	v_add_u32_e32 v142, s14, v130
	ds_read_b128 v[146:149], v142
	ds_read_b128 v[150:153], v142 offset:32
	ds_read_b128 v[154:157], v142 offset:64
	ds_read_b128 v[158:161], v142 offset:96
	ds_read_b128 v[130:133], v142 offset:128
	ds_read_b128 v[134:137], v142 offset:160
	ds_read_b128 v[138:141], v142 offset:192
	ds_read_b128 v[142:145], v142 offset:224
	s_waitcnt lgkmcnt(0)
	v_pk_mul_f32 v[126:127], v[126:127], v[158:159]
	v_pk_mul_f32 v[122:123], v[122:123], v[154:155]
	v_pk_mul_f32 v[118:119], v[118:119], v[150:151]
	v_pk_mul_f32 v[128:129], v[128:129], v[160:161]
	v_pk_mul_f32 v[124:125], v[124:125], v[156:157]
	v_pk_mul_f32 v[120:121], v[120:121], v[152:153]
	v_pk_mul_f32 v[116:117], v[116:117], v[148:149]
	v_pk_mul_f32 v[114:115], v[114:115], v[146:147]
	v_pk_mul_f32 v[110:111], v[110:111], v[158:159]
	v_pk_mul_f32 v[106:107], v[106:107], v[154:155]
	v_pk_mul_f32 v[102:103], v[102:103], v[150:151]
	v_pk_mul_f32 v[112:113], v[112:113], v[160:161]
	v_pk_mul_f32 v[108:109], v[108:109], v[156:157]
	v_pk_mul_f32 v[104:105], v[104:105], v[152:153]
	v_pk_mul_f32 v[100:101], v[100:101], v[148:149]
	v_pk_mul_f32 v[98:99], v[98:99], v[146:147]
	v_pk_mul_f32 v[94:95], v[94:95], v[158:159]
	v_pk_mul_f32 v[90:91], v[90:91], v[154:155]
	v_pk_mul_f32 v[86:87], v[86:87], v[150:151]
	v_pk_mul_f32 v[96:97], v[96:97], v[160:161]
	v_pk_mul_f32 v[92:93], v[92:93], v[156:157]
	v_pk_mul_f32 v[88:89], v[88:89], v[152:153]
	v_pk_mul_f32 v[84:85], v[84:85], v[148:149]
	v_pk_mul_f32 v[82:83], v[82:83], v[146:147]
	v_pk_mul_f32 v[62:63], v[62:63], v[158:159]
	v_pk_mul_f32 v[58:59], v[58:59], v[154:155]
	v_pk_mul_f32 v[54:55], v[54:55], v[150:151]
	v_pk_mul_f32 v[64:65], v[64:65], v[160:161]
	v_pk_mul_f32 v[60:61], v[60:61], v[156:157]
	v_pk_mul_f32 v[56:57], v[56:57], v[152:153]
	v_pk_mul_f32 v[52:53], v[52:53], v[148:149]
	v_pk_mul_f32 v[50:51], v[50:51], v[146:147]
	v_pk_mul_f32 v[14:15], v[14:15], v[142:143]
	v_pk_mul_f32 v[10:11], v[10:11], v[138:139]
	v_pk_mul_f32 v[6:7], v[6:7], v[134:135]
	v_pk_mul_f32 v[16:17], v[16:17], v[144:145]
	v_pk_mul_f32 v[12:13], v[12:13], v[140:141]
	v_pk_mul_f32 v[8:9], v[8:9], v[136:137]
	v_pk_mul_f32 v[4:5], v[4:5], v[132:133]
	v_pk_mul_f32 v[2:3], v[2:3], v[130:131]
	v_pk_mul_f32 v[78:79], v[78:79], v[142:143]
	v_pk_mul_f32 v[74:75], v[74:75], v[138:139]
	v_pk_mul_f32 v[70:71], v[70:71], v[134:135]
	v_pk_mul_f32 v[80:81], v[80:81], v[144:145]
	v_pk_mul_f32 v[76:77], v[76:77], v[140:141]
	v_pk_mul_f32 v[72:73], v[72:73], v[136:137]
	v_pk_mul_f32 v[68:69], v[68:69], v[132:133]
	v_pk_mul_f32 v[66:67], v[66:67], v[130:131]
	v_pk_mul_f32 v[46:47], v[46:47], v[142:143]
	v_pk_mul_f32 v[42:43], v[42:43], v[138:139]
	v_pk_mul_f32 v[38:39], v[38:39], v[134:135]
	v_pk_mul_f32 v[48:49], v[48:49], v[144:145]
	v_pk_mul_f32 v[44:45], v[44:45], v[140:141]
	v_pk_mul_f32 v[40:41], v[40:41], v[136:137]
	v_pk_mul_f32 v[36:37], v[36:37], v[132:133]
	v_pk_mul_f32 v[34:35], v[34:35], v[130:131]
	v_pk_mul_f32 v[30:31], v[30:31], v[142:143]
	v_pk_mul_f32 v[26:27], v[26:27], v[138:139]
	v_pk_mul_f32 v[22:23], v[22:23], v[134:135]
	v_pk_mul_f32 v[32:33], v[32:33], v[144:145]
	v_pk_mul_f32 v[28:29], v[28:29], v[140:141]
	v_pk_mul_f32 v[24:25], v[24:25], v[136:137]
	v_pk_mul_f32 v[20:21], v[20:21], v[132:133]
	v_pk_mul_f32 v[18:19], v[18:19], v[130:131]

.LBB0_741:
	s_setprio 0
	v_mbcnt_lo_u32_b32 v0, -1, 0
	v_mbcnt_hi_u32_b32 v0, -1, v0
	s_nop 0
	v_cmp_gt_u32_e32 vcc, 32, v0
	s_and_saveexec_b64 s[4:5], vcc
	v_lshl_add_u32 v130, v0, 2, s14
	ds_write2_b32 v130, v202, v203 offset0:64 offset1:96
	s_or_b64 exec, exec, s[4:5]
	v_ashrrev_i32_e32 v134, 5, v0
	s_waitcnt lgkmcnt(0)
	v_lshl_add_u32 v139, v134, 4, s14
	ds_read_b128 v[140:143], v139 offset:256
	ds_read_b128 v[130:133], v139 offset:288
	ds_read_b128 v[144:147], v139 offset:384
	v_readlane_b32 s2, v255, 35
	v_and_b32_e32 v0, 31, v0
	s_waitcnt lgkmcnt(2)
	v_rcp_f32_e32 v140, v140
	s_waitcnt lgkmcnt(0)
	v_rcp_f32_e32 v135, v144
	s_nop 0
	v_mul_f32_e32 v144, s2, v135
	v_mul_f32_e32 v2, v2, v144
	v_fma_f32 v137, v114, v140, -v2
	v_mul_f32_e32 v2, v66, v144
	v_fma_f32 v136, v98, v140, -v2
	v_mul_f32_e32 v2, v34, v144
	v_fma_f32 v135, v82, v140, -v2
	v_mul_f32_e32 v2, v18, v144
	v_rcp_f32_e32 v18, v145
	v_fma_f32 v114, v50, v140, -v2
	v_rcp_f32_e32 v2, v141
	v_mul_f32_e32 v138, v136, v136
	v_mul_f32_e32 v18, s2, v18
	v_mul_f32_e32 v3, v3, v18
	v_fma_f32 v98, v115, v2, -v3
	v_mul_f32_e32 v3, v67, v18
	v_fma_f32 v82, v99, v2, -v3
	v_mul_f32_e32 v3, v35, v18
	v_fma_f32 v67, v83, v2, -v3
	v_mul_f32_e32 v3, v19, v18
	v_fma_f32 v66, v51, v2, -v3
	v_rcp_f32_e32 v3, v146
	v_rcp_f32_e32 v2, v142
	v_fmac_f32_e32 v138, v137, v137
	v_fmac_f32_e32 v138, v135, v135
	v_mul_f32_e32 v3, s2, v3
	v_mul_f32_e32 v4, v4, v3
	v_fma_f32 v51, v116, v2, -v4
	v_mul_f32_e32 v4, v68, v3
	v_fma_f32 v50, v100, v2, -v4
	v_mul_f32_e32 v4, v36, v3
	v_mul_f32_e32 v3, v20, v3
	v_fma_f32 v35, v52, v2, -v3
	v_rcp_f32_e32 v3, v147
	v_fma_f32 v36, v84, v2, -v4
	v_rcp_f32_e32 v2, v143
	v_fmac_f32_e32 v138, v114, v114
	v_mul_f32_e32 v3, s2, v3
	v_mul_f32_e32 v4, v5, v3
	v_fma_f32 v34, v117, v2, -v4
	v_mul_f32_e32 v4, v69, v3
	v_fma_f32 v20, v101, v2, -v4
	v_mul_f32_e32 v4, v37, v3
	v_mul_f32_e32 v3, v21, v3
	v_fma_f32 v19, v85, v2, -v4
	v_fma_f32 v18, v53, v2, -v3
	ds_read_b128 v[2:5], v139 offset:416
	v_rcp_f32_e32 v21, v130
	v_mul_f32_e32 v115, v82, v82
	v_fmac_f32_e32 v115, v98, v98
	v_fmac_f32_e32 v115, v67, v67
	s_waitcnt lgkmcnt(0)
	v_rcp_f32_e32 v2, v2
	v_rcp_f32_e32 v3, v3
	v_fmac_f32_e32 v115, v66, v66
	v_mul_f32_e32 v99, v50, v50
	v_mul_f32_e32 v2, s2, v2
	v_mul_f32_e32 v6, v6, v2
	v_fma_f32 v52, v118, v21, -v6
	v_mul_f32_e32 v6, v70, v2
	v_fma_f32 v37, v102, v21, -v6
	v_mul_f32_e32 v6, v38, v2
	v_mul_f32_e32 v2, v22, v2
	v_fma_f32 v38, v86, v21, -v6
	v_fma_f32 v21, v54, v21, -v2
	v_rcp_f32_e32 v2, v131
	v_mul_f32_e32 v3, s2, v3
	v_mul_f32_e32 v6, v7, v3
	v_fmac_f32_e32 v99, v51, v51
	v_fma_f32 v54, v119, v2, -v6
	v_mul_f32_e32 v6, v71, v3
	v_fma_f32 v53, v103, v2, -v6
	v_mul_f32_e32 v6, v39, v3
	v_mul_f32_e32 v3, v23, v3
	v_fma_f32 v22, v55, v2, -v3
	v_rcp_f32_e32 v3, v4
	v_fma_f32 v39, v87, v2, -v6
	v_rcp_f32_e32 v2, v132
	v_fmac_f32_e32 v99, v36, v36
	v_mul_f32_e32 v3, s2, v3
	v_mul_f32_e32 v4, v8, v3
	v_fma_f32 v69, v120, v2, -v4
	v_mul_f32_e32 v4, v72, v3
	v_fma_f32 v55, v104, v2, -v4
	v_mul_f32_e32 v4, v40, v3
	v_mul_f32_e32 v3, v24, v3
	v_fma_f32 v40, v56, v2, -v3
	v_rcp_f32_e32 v3, v5
	v_fma_f32 v68, v88, v2, -v4
	v_rcp_f32_e32 v2, v133
	v_fmac_f32_e32 v99, v35, v35
	v_mul_f32_e32 v3, s2, v3
	v_mul_f32_e32 v4, v9, v3
	v_fma_f32 v72, v121, v2, -v4
	v_mul_f32_e32 v4, v73, v3
	v_fma_f32 v70, v105, v2, -v4
	v_mul_f32_e32 v4, v41, v3
	v_mul_f32_e32 v3, v25, v3
	v_fma_f32 v71, v89, v2, -v4
	v_fma_f32 v56, v57, v2, -v3
	ds_read_b128 v[2:5], v139 offset:320
	ds_read_b128 v[6:9], v139 offset:448
	v_mul_f32_e32 v84, v20, v20
	v_fmac_f32_e32 v84, v34, v34
	v_fmac_f32_e32 v84, v19, v19
	s_waitcnt lgkmcnt(1)
	v_rcp_f32_e32 v2, v2
	s_waitcnt lgkmcnt(0)
	v_rcp_f32_e32 v6, v6
	v_fmac_f32_e32 v84, v18, v18
	v_mul_f32_e32 v101, v37, v37
	v_fmac_f32_e32 v101, v52, v52
	v_mul_f32_e32 v6, s2, v6
	v_mul_f32_e32 v10, v10, v6
	v_fma_f32 v83, v122, v2, -v10
	v_mul_f32_e32 v10, v74, v6
	v_fma_f32 v74, v106, v2, -v10
	v_mul_f32_e32 v10, v42, v6
	v_mul_f32_e32 v6, v26, v6
	v_fma_f32 v73, v90, v2, -v10
	v_fma_f32 v58, v58, v2, -v6
	v_rcp_f32_e32 v2, v3
	v_rcp_f32_e32 v3, v7
	v_fmac_f32_e32 v101, v38, v38
	v_fmac_f32_e32 v101, v21, v21
	v_mul_f32_e32 v100, v53, v53
	v_mul_f32_e32 v3, s2, v3
	v_mul_f32_e32 v6, v11, v3
	v_fma_f32 v57, v123, v2, -v6
	v_mul_f32_e32 v6, v75, v3
	v_fma_f32 v42, v107, v2, -v6
	v_mul_f32_e32 v6, v43, v3
	v_mul_f32_e32 v3, v27, v3
	v_fma_f32 v27, v59, v2, -v3
	v_rcp_f32_e32 v3, v8
	v_fma_f32 v41, v91, v2, -v6
	v_rcp_f32_e32 v2, v4
	v_fmac_f32_e32 v100, v54, v54
	v_mul_f32_e32 v3, s2, v3
	v_mul_f32_e32 v4, v12, v3
	v_fma_f32 v26, v124, v2, -v4
	v_mul_f32_e32 v4, v76, v3
	v_fma_f32 v25, v108, v2, -v4
	v_mul_f32_e32 v4, v44, v3
	v_mul_f32_e32 v3, v28, v3
	v_fma_f32 v23, v60, v2, -v3
	v_rcp_f32_e32 v3, v9
	v_fma_f32 v24, v92, v2, -v4
	v_rcp_f32_e32 v2, v5
	ds_read_b128 v[6:9], v139 offset:480
	v_mul_f32_e32 v3, s2, v3
	v_mul_f32_e32 v4, v13, v3
	v_fma_f32 v13, v125, v2, -v4
	v_mul_f32_e32 v4, v77, v3
	v_fma_f32 v12, v109, v2, -v4
	v_mul_f32_e32 v4, v45, v3
	v_mul_f32_e32 v3, v29, v3
	v_fma_f32 v11, v93, v2, -v4
	v_fma_f32 v10, v61, v2, -v3
	ds_read_b128 v[2:5], v139 offset:352
	s_waitcnt lgkmcnt(1)
	v_rcp_f32_e32 v7, v7
	v_fmac_f32_e32 v100, v39, v39
	v_fmac_f32_e32 v100, v22, v22
	v_mul_f32_e32 v87, v55, v55
	s_waitcnt lgkmcnt(0)
	v_rcp_f32_e32 v43, v2
	v_rcp_f32_e32 v2, v6
	v_rcp_f32_e32 v3, v3
	v_mul_f32_e32 v7, s2, v7
	v_mul_f32_e32 v15, v15, v7
	v_mul_f32_e32 v6, s2, v2
	v_mul_f32_e32 v2, v14, v6
	v_fma_f32 v29, v126, v43, -v2
	v_mul_f32_e32 v2, v78, v6
	v_mul_f32_e32 v28, v46, v6
	v_mul_f32_e32 v6, v30, v6
	v_fma_f32 v14, v110, v43, -v2
	v_fma_f32 v28, v94, v43, -v28
	v_fma_f32 v6, v62, v43, -v6
	v_fma_f32 v43, v127, v3, -v15
	v_mul_f32_e32 v15, v79, v7
	v_mul_f32_e32 v30, v47, v7
	v_mul_f32_e32 v7, v31, v7
	v_fma_f32 v15, v111, v3, -v15
	v_fma_f32 v30, v95, v3, -v30
	v_fma_f32 v7, v63, v3, -v7
	v_rcp_f32_e32 v3, v4
	v_rcp_f32_e32 v4, v8
	v_fmac_f32_e32 v87, v69, v69
	v_fmac_f32_e32 v87, v68, v68
	v_fmac_f32_e32 v87, v40, v40
	v_mul_f32_e32 v4, s2, v4
	v_mul_f32_e32 v8, v16, v4
	v_fma_f32 v31, v128, v3, -v8
	v_mul_f32_e32 v8, v80, v4
	v_mul_f32_e32 v16, v48, v4
	v_mul_f32_e32 v4, v32, v4
	v_fma_f32 v8, v112, v3, -v8
	v_fma_f32 v16, v96, v3, -v16
	v_fma_f32 v4, v64, v3, -v4
	v_rcp_f32_e32 v3, v5
	v_rcp_f32_e32 v5, v9
	v_mul_f32_e32 v86, v70, v70
	v_fmac_f32_e32 v86, v72, v72
	v_fmac_f32_e32 v86, v71, v71
	v_mul_f32_e32 v5, s2, v5
	v_mul_f32_e32 v9, v17, v5
	v_fma_f32 v32, v129, v3, -v9
	v_mul_f32_e32 v9, v81, v5
	v_fma_f32 v17, v113, v3, -v9
	v_mul_f32_e32 v9, v49, v5
	v_mul_f32_e32 v5, v33, v5
	v_fma_f32 v9, v97, v3, -v9
	v_fma_f32 v5, v65, v3, -v5
	ds_swizzle_b32 v3, v138 offset:swizzle(SWAP,1)
	v_fmac_f32_e32 v86, v56, v56
	v_mul_f32_e32 v85, v74, v74
	v_fmac_f32_e32 v85, v83, v83
	v_fmac_f32_e32 v85, v73, v73
	s_waitcnt lgkmcnt(0)
	v_add_f32_e32 v3, v138, v3
	ds_swizzle_b32 v33, v3 offset:swizzle(SWAP,2)
	v_fmac_f32_e32 v85, v58, v58
	v_mul_f32_e32 v75, v42, v42
	v_fmac_f32_e32 v75, v57, v57
	v_fmac_f32_e32 v75, v41, v41
	s_waitcnt lgkmcnt(0)
	v_add_f32_e32 v3, v3, v33
	ds_swizzle_b32 v33, v3 offset:swizzle(SWAP,4)
	v_fmac_f32_e32 v75, v27, v27
	v_mul_f32_e32 v59, v25, v25
	v_fmac_f32_e32 v59, v26, v26
	v_fmac_f32_e32 v59, v24, v24
	s_waitcnt lgkmcnt(0)
	v_add_f32_e32 v3, v3, v33
	ds_swizzle_b32 v33, v3 offset:swizzle(SWAP,8)
	v_fmac_f32_e32 v59, v23, v23
	v_mul_f32_e32 v44, v12, v12
	v_fmac_f32_e32 v44, v13, v13
	v_fmac_f32_e32 v44, v11, v11
	s_waitcnt lgkmcnt(0)
	v_add_f32_e32 v3, v3, v33
	ds_swizzle_b32 v33, v3 offset:swizzle(SWAP,16)
	v_fmac_f32_e32 v44, v10, v10
	v_mul_f32_e32 v2, v14, v14
	v_fmac_f32_e32 v2, v29, v29
	v_fmac_f32_e32 v2, v28, v28
	s_waitcnt lgkmcnt(0)
	v_add_f32_e32 v3, v3, v33
	ds_swizzle_b32 v33, v115 offset:swizzle(SWAP,1)
	v_fmac_f32_e32 v2, v6, v6
	v_mul_f32_e32 v76, v15, v15
	v_fmac_f32_e32 v76, v43, v43
	v_fmac_f32_e32 v76, v30, v30
	s_waitcnt lgkmcnt(0)
	v_add_f32_e32 v33, v115, v33
	ds_swizzle_b32 v45, v33 offset:swizzle(SWAP,2)
	v_fmac_f32_e32 v76, v7, v7
	v_mul_f32_e32 v77, v8, v8
	v_fmac_f32_e32 v77, v31, v31
	v_fmac_f32_e32 v77, v16, v16
	s_waitcnt lgkmcnt(0)
	v_add_f32_e32 v33, v33, v45
	ds_swizzle_b32 v45, v33 offset:swizzle(SWAP,4)
	v_fmac_f32_e32 v77, v4, v4
	v_mul_f32_e32 v78, v17, v17
	v_fmac_f32_e32 v78, v32, v32
	v_fmac_f32_e32 v78, v9, v9
	s_waitcnt lgkmcnt(0)
	v_add_f32_e32 v33, v33, v45
	ds_swizzle_b32 v45, v33 offset:swizzle(SWAP,8)
	v_fmac_f32_e32 v78, v5, v5
	v_readlane_b32 s2, v255, 16
	v_readlane_b32 s3, v255, 17
	s_waitcnt lgkmcnt(0)
	v_add_f32_e32 v33, v33, v45
	ds_swizzle_b32 v45, v33 offset:swizzle(SWAP,16)
	s_cmp_eq_u32 s2, 0
	v_readlane_b32 s2, v255, 26
	v_lshlrev_b32_e32 v79, 2, v0
	v_readlane_b32 s3, v255, 27
	s_waitcnt lgkmcnt(0)
	v_add_f32_e32 v33, v33, v45
	ds_swizzle_b32 v45, v99 offset:swizzle(SWAP,1)
	v_fmamk_f32 v3, v3, 0x3c000000, v244
	s_cselect_b64 vcc, -1, 0
	s_lshl_b32 s36, s1, 1
	v_lshlrev_b32_e32 v0, 1, v0
	s_waitcnt lgkmcnt(0)
	v_add_f32_e32 v45, v99, v45
	ds_swizzle_b32 v46, v45 offset:swizzle(SWAP,2)
	s_waitcnt lgkmcnt(0)
	v_add_f32_e32 v45, v45, v46
	ds_swizzle_b32 v46, v45 offset:swizzle(SWAP,4)
	s_waitcnt lgkmcnt(0)
	v_add_f32_e32 v45, v45, v46
	ds_swizzle_b32 v46, v45 offset:swizzle(SWAP,8)
	s_waitcnt lgkmcnt(0)
	v_add_f32_e32 v45, v45, v46
	ds_swizzle_b32 v46, v45 offset:swizzle(SWAP,16)
	s_waitcnt lgkmcnt(0)
	v_add_f32_e32 v45, v45, v46
	ds_swizzle_b32 v46, v84 offset:swizzle(SWAP,1)
	s_waitcnt lgkmcnt(0)
	v_add_f32_e32 v46, v84, v46
	ds_swizzle_b32 v47, v46 offset:swizzle(SWAP,2)
	v_rsq_f32_e32 v84, v3
	s_waitcnt lgkmcnt(0)
	v_add_f32_e32 v46, v46, v47
	ds_swizzle_b32 v47, v46 offset:swizzle(SWAP,4)
	s_waitcnt lgkmcnt(0)
	v_add_f32_e32 v46, v46, v47
	ds_swizzle_b32 v47, v46 offset:swizzle(SWAP,8)
	s_waitcnt lgkmcnt(0)
	v_add_f32_e32 v46, v46, v47
	ds_swizzle_b32 v47, v46 offset:swizzle(SWAP,16)
	s_waitcnt lgkmcnt(0)
	v_add_f32_e32 v46, v46, v47
	ds_swizzle_b32 v47, v101 offset:swizzle(SWAP,1)
	s_waitcnt lgkmcnt(0)
	v_add_f32_e32 v47, v101, v47
	ds_swizzle_b32 v48, v47 offset:swizzle(SWAP,2)
	s_waitcnt lgkmcnt(0)
	v_add_f32_e32 v47, v47, v48
	ds_swizzle_b32 v48, v47 offset:swizzle(SWAP,4)
	s_waitcnt lgkmcnt(0)
	v_add_f32_e32 v47, v47, v48
	ds_swizzle_b32 v48, v47 offset:swizzle(SWAP,8)
	s_waitcnt lgkmcnt(0)
	v_add_f32_e32 v47, v47, v48
	ds_swizzle_b32 v48, v47 offset:swizzle(SWAP,16)
	s_waitcnt lgkmcnt(0)
	v_add_f32_e32 v47, v47, v48
	ds_swizzle_b32 v48, v100 offset:swizzle(SWAP,1)
	s_waitcnt lgkmcnt(0)
	v_add_f32_e32 v48, v100, v48
	ds_swizzle_b32 v49, v48 offset:swizzle(SWAP,2)
	s_waitcnt lgkmcnt(0)
	v_add_f32_e32 v48, v48, v49
	ds_swizzle_b32 v49, v48 offset:swizzle(SWAP,4)
	s_waitcnt lgkmcnt(0)
	v_add_f32_e32 v48, v48, v49
	ds_swizzle_b32 v49, v48 offset:swizzle(SWAP,8)
	s_waitcnt lgkmcnt(0)
	v_add_f32_e32 v48, v48, v49
	ds_swizzle_b32 v49, v48 offset:swizzle(SWAP,16)
	s_waitcnt lgkmcnt(0)
	v_add_f32_e32 v48, v48, v49
	ds_swizzle_b32 v49, v87 offset:swizzle(SWAP,1)
	s_waitcnt lgkmcnt(0)
	v_add_f32_e32 v49, v87, v49
	ds_swizzle_b32 v60, v49 offset:swizzle(SWAP,2)
	s_waitcnt lgkmcnt(0)
	v_add_f32_e32 v49, v49, v60
	ds_swizzle_b32 v60, v49 offset:swizzle(SWAP,4)
	s_waitcnt lgkmcnt(0)
	v_add_f32_e32 v49, v49, v60
	ds_swizzle_b32 v60, v49 offset:swizzle(SWAP,8)
	s_waitcnt lgkmcnt(0)
	v_add_f32_e32 v49, v49, v60
	ds_swizzle_b32 v60, v49 offset:swizzle(SWAP,16)
	s_waitcnt lgkmcnt(0)
	v_add_f32_e32 v60, v49, v60
	ds_swizzle_b32 v49, v86 offset:swizzle(SWAP,1)
	s_waitcnt lgkmcnt(0)
	v_add_f32_e32 v49, v86, v49
	ds_swizzle_b32 v61, v49 offset:swizzle(SWAP,2)
	s_waitcnt lgkmcnt(0)
	v_add_f32_e32 v49, v49, v61
	ds_swizzle_b32 v61, v49 offset:swizzle(SWAP,4)
	s_waitcnt lgkmcnt(0)
	v_add_f32_e32 v49, v49, v61
	ds_swizzle_b32 v61, v49 offset:swizzle(SWAP,8)
	s_waitcnt lgkmcnt(0)
	v_add_f32_e32 v49, v49, v61
	ds_swizzle_b32 v61, v49 offset:swizzle(SWAP,16)
	s_waitcnt lgkmcnt(0)
	v_add_f32_e32 v62, v49, v61
	ds_swizzle_b32 v49, v85 offset:swizzle(SWAP,1)
	s_waitcnt lgkmcnt(0)
	v_add_f32_e32 v49, v85, v49
	ds_swizzle_b32 v61, v49 offset:swizzle(SWAP,2)
	s_waitcnt lgkmcnt(0)
	v_add_f32_e32 v49, v49, v61
	ds_swizzle_b32 v61, v49 offset:swizzle(SWAP,4)
	s_waitcnt lgkmcnt(0)
	v_add_f32_e32 v49, v49, v61
	ds_swizzle_b32 v61, v49 offset:swizzle(SWAP,8)
	s_waitcnt lgkmcnt(0)
	v_add_f32_e32 v49, v49, v61
	ds_swizzle_b32 v61, v49 offset:swizzle(SWAP,16)
	s_waitcnt lgkmcnt(0)
	v_add_f32_e32 v64, v49, v61
	ds_swizzle_b32 v49, v75 offset:swizzle(SWAP,1)
	s_waitcnt lgkmcnt(0)
	v_add_f32_e32 v49, v75, v49
	ds_swizzle_b32 v61, v49 offset:swizzle(SWAP,2)
	s_waitcnt lgkmcnt(0)
	v_add_f32_e32 v49, v49, v61
	ds_swizzle_b32 v61, v49 offset:swizzle(SWAP,4)
	s_waitcnt lgkmcnt(0)
	v_add_f32_e32 v49, v49, v61
	ds_swizzle_b32 v61, v49 offset:swizzle(SWAP,8)
	s_waitcnt lgkmcnt(0)
	v_add_f32_e32 v49, v49, v61
	ds_swizzle_b32 v61, v49 offset:swizzle(SWAP,16)
	s_waitcnt lgkmcnt(0)
	v_add_f32_e32 v75, v49, v61
	ds_swizzle_b32 v49, v59 offset:swizzle(SWAP,1)
	s_waitcnt lgkmcnt(0)
	v_add_f32_e32 v49, v59, v49
	ds_swizzle_b32 v59, v49 offset:swizzle(SWAP,2)
	s_waitcnt lgkmcnt(0)
	v_add_f32_e32 v49, v49, v59
	ds_swizzle_b32 v59, v49 offset:swizzle(SWAP,4)
	s_waitcnt lgkmcnt(0)
	v_add_f32_e32 v49, v49, v59
	ds_swizzle_b32 v59, v49 offset:swizzle(SWAP,8)
	s_waitcnt lgkmcnt(0)
	v_add_f32_e32 v49, v49, v59
	ds_swizzle_b32 v59, v49 offset:swizzle(SWAP,16)
	s_waitcnt lgkmcnt(0)
	v_add_f32_e32 v65, v49, v59
	ds_swizzle_b32 v49, v44 offset:swizzle(SWAP,1)
	s_waitcnt lgkmcnt(0)
	v_add_f32_e32 v44, v44, v49
	ds_swizzle_b32 v49, v44 offset:swizzle(SWAP,2)
	s_waitcnt lgkmcnt(0)
	v_add_f32_e32 v44, v44, v49
	ds_swizzle_b32 v49, v44 offset:swizzle(SWAP,4)
	s_waitcnt lgkmcnt(0)
	v_add_f32_e32 v44, v44, v49
	ds_swizzle_b32 v49, v44 offset:swizzle(SWAP,8)
	s_waitcnt lgkmcnt(0)
	v_add_f32_e32 v44, v44, v49
	ds_swizzle_b32 v49, v44 offset:swizzle(SWAP,16)
	s_waitcnt lgkmcnt(0)
	v_add_f32_e32 v63, v44, v49
	ds_swizzle_b32 v44, v2 offset:swizzle(SWAP,1)
	s_waitcnt lgkmcnt(0)
	v_add_f32_e32 v2, v2, v44
	ds_swizzle_b32 v44, v2 offset:swizzle(SWAP,2)
	s_waitcnt lgkmcnt(0)
	v_add_f32_e32 v2, v2, v44
	ds_swizzle_b32 v44, v2 offset:swizzle(SWAP,4)
	s_waitcnt lgkmcnt(0)
	v_add_f32_e32 v2, v2, v44
	ds_swizzle_b32 v44, v2 offset:swizzle(SWAP,8)
	s_waitcnt lgkmcnt(0)
	v_add_f32_e32 v2, v2, v44
	ds_swizzle_b32 v44, v2 offset:swizzle(SWAP,16)
	s_waitcnt lgkmcnt(0)
	v_add_f32_e32 v61, v2, v44
	ds_swizzle_b32 v2, v76 offset:swizzle(SWAP,1)
	s_waitcnt lgkmcnt(0)
	v_add_f32_e32 v2, v76, v2
	ds_swizzle_b32 v44, v2 offset:swizzle(SWAP,2)
	global_load_dword v76, v79, s[2:3]
	s_waitcnt lgkmcnt(0)
	v_add_f32_e32 v2, v2, v44
	ds_swizzle_b32 v44, v2 offset:swizzle(SWAP,4)
	s_waitcnt lgkmcnt(0)
	v_add_f32_e32 v2, v2, v44
	ds_swizzle_b32 v44, v2 offset:swizzle(SWAP,8)
	s_waitcnt lgkmcnt(0)
	v_add_f32_e32 v2, v2, v44
	ds_swizzle_b32 v44, v2 offset:swizzle(SWAP,16)
	s_waitcnt lgkmcnt(0)
	v_add_f32_e32 v59, v2, v44
	ds_swizzle_b32 v2, v77 offset:swizzle(SWAP,1)
	s_waitcnt lgkmcnt(0)
	v_add_f32_e32 v2, v77, v2
	ds_swizzle_b32 v44, v2 offset:swizzle(SWAP,2)
	global_load_dword v77, v79, s[2:3] offset:128
	s_waitcnt lgkmcnt(0)
	v_add_f32_e32 v2, v2, v44
	ds_swizzle_b32 v44, v2 offset:swizzle(SWAP,4)
	s_waitcnt lgkmcnt(0)
	v_add_f32_e32 v2, v2, v44
	ds_swizzle_b32 v44, v2 offset:swizzle(SWAP,8)
	s_waitcnt lgkmcnt(0)
	v_add_f32_e32 v2, v2, v44
	ds_swizzle_b32 v44, v2 offset:swizzle(SWAP,16)
	s_waitcnt lgkmcnt(0)
	v_add_f32_e32 v49, v2, v44
	ds_swizzle_b32 v2, v78 offset:swizzle(SWAP,1)
	s_waitcnt lgkmcnt(0)
	v_add_f32_e32 v2, v78, v2
	global_load_dword v78, v79, s[2:3] offset:256
	ds_swizzle_b32 v44, v2 offset:swizzle(SWAP,2)
	global_load_dword v79, v79, s[2:3] offset:384
	v_readlane_b32 s2, v254, 63
	v_readlane_b32 s3, v255, 0
	s_waitcnt lgkmcnt(0)
	v_add_f32_e32 v2, v2, v44
	ds_swizzle_b32 v44, v2 offset:swizzle(SWAP,4)
	s_waitcnt lgkmcnt(0)
	v_add_f32_e32 v2, v2, v44
	ds_swizzle_b32 v44, v2 offset:swizzle(SWAP,8)
	s_waitcnt lgkmcnt(0)
	v_add_f32_e32 v2, v2, v44
	ds_swizzle_b32 v44, v2 offset:swizzle(SWAP,16)
	s_waitcnt lgkmcnt(0)
	v_add_f32_e32 v44, v2, v44
	v_cndmask_b32_e32 v2, v252, v246, vcc
	s_waitcnt vmcnt(3)
	v_mul_f32_e32 v76, v76, v2
	s_waitcnt vmcnt(2)
	v_mul_f32_e32 v77, v2, v77
	s_waitcnt vmcnt(1)
	v_mul_f32_e32 v78, v2, v78
	s_waitcnt vmcnt(0)
	v_mul_f32_e32 v79, v2, v79
	v_lshl_add_u32 v2, v134, 2, s0
	v_ashrrev_i32_e32 v3, 31, v2
	v_lshlrev_b64 v[80:81], 11, v[2:3]
	v_mul_f32_e32 v3, v137, v84
	v_lshl_add_u64 v[80:81], s[2:3], 0, v[80:81]
	v_mul_f32_e32 v3, v3, v76
	v_lshl_add_u64 v[80:81], v[80:81], 0, s[36:37]
	v_bfe_u32 v85, v3, 16, 1
	v_lshl_add_u64 v[80:81], v[80:81], 0, v[0:1]
	v_add3_u32 v3, v3, v85, s86
	global_store_short_d16_hi v[80:81], v3, off offset:1024
	v_mul_f32_e32 v3, v136, v84
	v_mul_f32_e32 v3, v3, v77
	v_bfe_u32 v85, v3, 16, 1
	v_add3_u32 v3, v3, v85, s86
	global_store_short_d16_hi v[80:81], v3, off offset:1088
	v_mul_f32_e32 v3, v135, v84
	v_mul_f32_e32 v3, v3, v78
	v_bfe_u32 v85, v3, 16, 1
	v_add3_u32 v3, v3, v85, s86
	global_store_short_d16_hi v[80:81], v3, off offset:1152
	v_mul_f32_e32 v3, v114, v84
	v_mul_f32_e32 v3, v3, v79
	v_bfe_u32 v84, v3, 16, 1
	v_add3_u32 v3, v3, v84, s86
	global_store_short_d16_hi v[80:81], v3, off offset:1216
	v_fmamk_f32 v3, v33, 0x3c000000, v244
	v_rsq_f32_e32 v3, v3
	v_or_b32_e32 v80, 1, v2
	v_ashrrev_i32_e32 v81, 31, v80
	v_lshlrev_b64 v[80:81], 11, v[80:81]
	v_mul_f32_e32 v33, v98, v3
	v_lshl_add_u64 v[80:81], s[2:3], 0, v[80:81]
	v_mul_f32_e32 v33, v33, v76
	v_lshl_add_u64 v[80:81], v[80:81], 0, s[36:37]
	v_bfe_u32 v84, v33, 16, 1
	v_lshl_add_u64 v[80:81], v[80:81], 0, v[0:1]
	v_add3_u32 v33, v33, v84, s86
	global_store_short_d16_hi v[80:81], v33, off offset:1024
	v_mul_f32_e32 v33, v82, v3
	v_mul_f32_e32 v33, v33, v77
	v_bfe_u32 v82, v33, 16, 1
	v_add3_u32 v33, v33, v82, s86
	global_store_short_d16_hi v[80:81], v33, off offset:1088
	v_mul_f32_e32 v33, v67, v3
	v_mul_f32_e32 v33, v33, v78
	v_bfe_u32 v67, v33, 16, 1
	v_mul_f32_e32 v3, v66, v3
	v_add3_u32 v33, v33, v67, s86
	v_mul_f32_e32 v3, v3, v79
	global_store_short_d16_hi v[80:81], v33, off offset:1152
	v_bfe_u32 v33, v3, 16, 1
	v_add3_u32 v3, v3, v33, s86
	global_store_short_d16_hi v[80:81], v3, off offset:1216
	v_fmamk_f32 v3, v45, 0x3c000000, v244
	v_rsq_f32_e32 v3, v3
	v_or_b32_e32 v66, 2, v2
	v_ashrrev_i32_e32 v67, 31, v66
	v_lshlrev_b64 v[66:67], 11, v[66:67]
	v_mul_f32_e32 v33, v51, v3
	v_lshl_add_u64 v[66:67], s[2:3], 0, v[66:67]
	v_mul_f32_e32 v33, v33, v76
	v_lshl_add_u64 v[66:67], v[66:67], 0, s[36:37]
	v_bfe_u32 v45, v33, 16, 1
	v_lshl_add_u64 v[66:67], v[66:67], 0, v[0:1]
	v_add3_u32 v33, v33, v45, s86
	global_store_short_d16_hi v[66:67], v33, off offset:1024
	v_mul_f32_e32 v33, v50, v3
	v_mul_f32_e32 v33, v33, v77
	v_bfe_u32 v45, v33, 16, 1
	v_add3_u32 v33, v33, v45, s86
	global_store_short_d16_hi v[66:67], v33, off offset:1088
	v_mul_f32_e32 v33, v36, v3
	v_mul_f32_e32 v33, v33, v78
	v_bfe_u32 v36, v33, 16, 1
	v_mul_f32_e32 v3, v35, v3
	v_add3_u32 v33, v33, v36, s86
	v_mul_f32_e32 v3, v3, v79
	global_store_short_d16_hi v[66:67], v33, off offset:1152
	v_bfe_u32 v33, v3, 16, 1
	v_add3_u32 v3, v3, v33, s86
	global_store_short_d16_hi v[66:67], v3, off offset:1216
	v_fmamk_f32 v3, v46, 0x3c000000, v244
	v_rsq_f32_e32 v3, v3
	v_or_b32_e32 v50, 3, v2
	v_ashrrev_i32_e32 v51, 31, v50
	v_lshlrev_b64 v[50:51], 11, v[50:51]
	v_mul_f32_e32 v33, v34, v3
	v_mul_f32_e32 v20, v20, v3
	v_mul_f32_e32 v19, v19, v3
	v_mul_f32_e32 v3, v18, v3
	v_lshl_add_u64 v[50:51], s[2:3], 0, v[50:51]
	v_mul_f32_e32 v33, v33, v76
	v_mul_f32_e32 v3, v3, v79
	v_lshl_add_u64 v[50:51], v[50:51], 0, s[36:37]
	v_bfe_u32 v34, v33, 16, 1
	v_bfe_u32 v18, v3, 16, 1
	v_lshl_add_u64 v[50:51], v[50:51], 0, v[0:1]
	v_add3_u32 v33, v33, v34, s86
	v_mul_f32_e32 v20, v20, v77
	v_add3_u32 v3, v3, v18, s86
	global_store_short_d16_hi v[50:51], v33, off offset:1024
	v_bfe_u32 v33, v20, 16, 1
	global_store_short_d16_hi v[50:51], v3, off offset:1216
	v_fmamk_f32 v3, v47, 0x3c000000, v244
	v_add3_u32 v20, v20, v33, s86
	v_mul_f32_e32 v19, v19, v78
	v_rsq_f32_e32 v3, v3
	global_store_short_d16_hi v[50:51], v20, off offset:1088
	v_bfe_u32 v20, v19, 16, 1
	v_add3_u32 v19, v19, v20, s86
	v_add_u32_e32 v18, 8, v2
	global_store_short_d16_hi v[50:51], v19, off offset:1152
	v_ashrrev_i32_e32 v19, 31, v18
	v_lshlrev_b64 v[18:19], 11, v[18:19]
	v_mul_f32_e32 v20, v52, v3
	v_lshl_add_u64 v[18:19], s[2:3], 0, v[18:19]
	v_mul_f32_e32 v20, v20, v76
	v_lshl_add_u64 v[18:19], v[18:19], 0, s[36:37]
	v_bfe_u32 v33, v20, 16, 1
	v_lshl_add_u64 v[18:19], v[18:19], 0, v[0:1]
	v_add3_u32 v20, v20, v33, s86
	global_store_short_d16_hi v[18:19], v20, off offset:1024
	v_mul_f32_e32 v20, v37, v3
	v_mul_f32_e32 v20, v20, v77
	v_bfe_u32 v33, v20, 16, 1
	v_add3_u32 v20, v20, v33, s86
	global_store_short_d16_hi v[18:19], v20, off offset:1088
	v_mul_f32_e32 v20, v38, v3
	v_mul_f32_e32 v20, v20, v78
	v_bfe_u32 v33, v20, 16, 1
	v_mul_f32_e32 v3, v21, v3
	v_add3_u32 v20, v20, v33, s86
	v_mul_f32_e32 v3, v3, v79
	global_store_short_d16_hi v[18:19], v20, off offset:1152
	v_bfe_u32 v20, v3, 16, 1
	v_add3_u32 v3, v3, v20, s86
	global_store_short_d16_hi v[18:19], v3, off offset:1216
	v_fmamk_f32 v3, v48, 0x3c000000, v244
	v_rsq_f32_e32 v3, v3
	v_add_u32_e32 v18, 9, v2
	v_ashrrev_i32_e32 v19, 31, v18
	v_lshlrev_b64 v[18:19], 11, v[18:19]
	v_mul_f32_e32 v20, v54, v3
	v_lshl_add_u64 v[18:19], s[2:3], 0, v[18:19]
	v_mul_f32_e32 v20, v20, v76
	v_lshl_add_u64 v[18:19], v[18:19], 0, s[36:37]
	v_bfe_u32 v21, v20, 16, 1
	v_lshl_add_u64 v[18:19], v[18:19], 0, v[0:1]
	v_add3_u32 v20, v20, v21, s86
	global_store_short_d16_hi v[18:19], v20, off offset:1024
	v_mul_f32_e32 v20, v53, v3
	v_mul_f32_e32 v20, v20, v77
	v_bfe_u32 v21, v20, 16, 1
	v_add3_u32 v20, v20, v21, s86
	global_store_short_d16_hi v[18:19], v20, off offset:1088
	v_mul_f32_e32 v20, v39, v3
	v_mul_f32_e32 v20, v20, v78
	v_bfe_u32 v21, v20, 16, 1
	v_mul_f32_e32 v3, v22, v3
	v_add3_u32 v20, v20, v21, s86
	v_mul_f32_e32 v3, v3, v79
	global_store_short_d16_hi v[18:19], v20, off offset:1152
	v_bfe_u32 v20, v3, 16, 1
	v_add3_u32 v3, v3, v20, s86
	global_store_short_d16_hi v[18:19], v3, off offset:1216
	v_fmamk_f32 v3, v60, 0x3c000000, v244
	v_rsq_f32_e32 v3, v3
	v_add_u32_e32 v18, 10, v2
	v_ashrrev_i32_e32 v19, 31, v18
	v_lshlrev_b64 v[18:19], 11, v[18:19]
	v_mul_f32_e32 v20, v69, v3
	v_lshl_add_u64 v[18:19], s[2:3], 0, v[18:19]
	v_mul_f32_e32 v20, v20, v76
	v_lshl_add_u64 v[18:19], v[18:19], 0, s[36:37]
	v_bfe_u32 v21, v20, 16, 1
	v_lshl_add_u64 v[18:19], v[18:19], 0, v[0:1]
	v_add3_u32 v20, v20, v21, s86
	global_store_short_d16_hi v[18:19], v20, off offset:1024
	v_mul_f32_e32 v20, v55, v3
	v_mul_f32_e32 v20, v20, v77
	v_bfe_u32 v21, v20, 16, 1
	v_add3_u32 v20, v20, v21, s86
	global_store_short_d16_hi v[18:19], v20, off offset:1088
	v_mul_f32_e32 v20, v68, v3
	v_mul_f32_e32 v20, v20, v78
	v_bfe_u32 v21, v20, 16, 1
	v_mul_f32_e32 v3, v40, v3
	v_add3_u32 v20, v20, v21, s86
	v_mul_f32_e32 v3, v3, v79
	global_store_short_d16_hi v[18:19], v20, off offset:1152
	v_bfe_u32 v20, v3, 16, 1
	v_add3_u32 v3, v3, v20, s86
	global_store_short_d16_hi v[18:19], v3, off offset:1216
	v_fmamk_f32 v3, v62, 0x3c000000, v244
	v_rsq_f32_e32 v3, v3
	v_add_u32_e32 v18, 11, v2
	v_ashrrev_i32_e32 v19, 31, v18
	v_lshlrev_b64 v[18:19], 11, v[18:19]
	v_mul_f32_e32 v20, v72, v3
	v_lshl_add_u64 v[18:19], s[2:3], 0, v[18:19]
	v_mul_f32_e32 v20, v20, v76
	v_lshl_add_u64 v[18:19], v[18:19], 0, s[36:37]
	v_bfe_u32 v21, v20, 16, 1
	v_lshl_add_u64 v[18:19], v[18:19], 0, v[0:1]
	v_add3_u32 v20, v20, v21, s86
	global_store_short_d16_hi v[18:19], v20, off offset:1024
	v_mul_f32_e32 v20, v70, v3
	v_mul_f32_e32 v20, v20, v77
	v_bfe_u32 v21, v20, 16, 1
	v_add3_u32 v20, v20, v21, s86
	global_store_short_d16_hi v[18:19], v20, off offset:1088
	v_mul_f32_e32 v20, v71, v3
	v_mul_f32_e32 v20, v20, v78
	v_bfe_u32 v21, v20, 16, 1
	v_mul_f32_e32 v3, v56, v3
	v_add3_u32 v20, v20, v21, s86
	v_mul_f32_e32 v3, v3, v79
	global_store_short_d16_hi v[18:19], v20, off offset:1152
	v_bfe_u32 v20, v3, 16, 1
	v_add3_u32 v3, v3, v20, s86
	global_store_short_d16_hi v[18:19], v3, off offset:1216
	v_fmamk_f32 v3, v64, 0x3c000000, v244
	v_rsq_f32_e32 v3, v3
	v_add_u32_e32 v18, 16, v2
	v_ashrrev_i32_e32 v19, 31, v18
	v_lshlrev_b64 v[18:19], 11, v[18:19]
	v_mul_f32_e32 v20, v83, v3
	v_lshl_add_u64 v[18:19], s[2:3], 0, v[18:19]
	v_mul_f32_e32 v20, v20, v76
	v_lshl_add_u64 v[18:19], v[18:19], 0, s[36:37]
	v_bfe_u32 v21, v20, 16, 1
	v_lshl_add_u64 v[18:19], v[18:19], 0, v[0:1]
	v_add3_u32 v20, v20, v21, s86
	global_store_short_d16_hi v[18:19], v20, off offset:1024
	v_mul_f32_e32 v20, v74, v3
	v_mul_f32_e32 v20, v20, v77
	v_bfe_u32 v21, v20, 16, 1
	v_add3_u32 v20, v20, v21, s86
	global_store_short_d16_hi v[18:19], v20, off offset:1088
	v_mul_f32_e32 v20, v73, v3
	v_mul_f32_e32 v20, v20, v78
	v_bfe_u32 v21, v20, 16, 1
	v_mul_f32_e32 v3, v58, v3
	v_add3_u32 v20, v20, v21, s86
	v_mul_f32_e32 v3, v3, v79
	global_store_short_d16_hi v[18:19], v20, off offset:1152
	v_bfe_u32 v20, v3, 16, 1
	v_add3_u32 v3, v3, v20, s86
	global_store_short_d16_hi v[18:19], v3, off offset:1216
	v_fmamk_f32 v3, v75, 0x3c000000, v244
	v_rsq_f32_e32 v3, v3
	v_add_u32_e32 v18, 17, v2
	v_ashrrev_i32_e32 v19, 31, v18
	v_lshlrev_b64 v[18:19], 11, v[18:19]
	v_mul_f32_e32 v20, v57, v3
	v_lshl_add_u64 v[18:19], s[2:3], 0, v[18:19]
	v_mul_f32_e32 v20, v20, v76
	v_lshl_add_u64 v[18:19], v[18:19], 0, s[36:37]
	v_bfe_u32 v21, v20, 16, 1
	v_lshl_add_u64 v[18:19], v[18:19], 0, v[0:1]
	v_add3_u32 v20, v20, v21, s86
	global_store_short_d16_hi v[18:19], v20, off offset:1024
	v_mul_f32_e32 v20, v42, v3
	v_mul_f32_e32 v20, v20, v77
	v_bfe_u32 v21, v20, 16, 1
	v_add3_u32 v20, v20, v21, s86
	global_store_short_d16_hi v[18:19], v20, off offset:1088
	v_mul_f32_e32 v20, v41, v3
	v_mul_f32_e32 v20, v20, v78
	v_bfe_u32 v21, v20, 16, 1
	v_mul_f32_e32 v3, v27, v3
	v_add3_u32 v20, v20, v21, s86
	v_mul_f32_e32 v3, v3, v79
	global_store_short_d16_hi v[18:19], v20, off offset:1152
	v_bfe_u32 v20, v3, 16, 1
	v_add3_u32 v3, v3, v20, s86
	global_store_short_d16_hi v[18:19], v3, off offset:1216
	v_fmamk_f32 v3, v65, 0x3c000000, v244
	v_rsq_f32_e32 v3, v3
	v_add_u32_e32 v18, 18, v2
	v_ashrrev_i32_e32 v19, 31, v18
	v_lshlrev_b64 v[18:19], 11, v[18:19]
	v_mul_f32_e32 v20, v26, v3
	v_lshl_add_u64 v[18:19], s[2:3], 0, v[18:19]
	v_mul_f32_e32 v20, v20, v76
	v_lshl_add_u64 v[18:19], v[18:19], 0, s[36:37]
	v_bfe_u32 v21, v20, 16, 1
	v_lshl_add_u64 v[18:19], v[18:19], 0, v[0:1]
	v_add3_u32 v20, v20, v21, s86
	global_store_short_d16_hi v[18:19], v20, off offset:1024
	v_mul_f32_e32 v20, v25, v3
	v_mul_f32_e32 v20, v20, v77
	v_bfe_u32 v21, v20, 16, 1
	v_add3_u32 v20, v20, v21, s86
	global_store_short_d16_hi v[18:19], v20, off offset:1088
	v_mul_f32_e32 v20, v24, v3
	v_mul_f32_e32 v20, v20, v78
	v_bfe_u32 v21, v20, 16, 1
	v_mul_f32_e32 v3, v23, v3
	v_add3_u32 v20, v20, v21, s86
	v_mul_f32_e32 v3, v3, v79
	global_store_short_d16_hi v[18:19], v20, off offset:1152
	v_bfe_u32 v20, v3, 16, 1
	v_add3_u32 v3, v3, v20, s86
	global_store_short_d16_hi v[18:19], v3, off offset:1216
	v_fmamk_f32 v3, v63, 0x3c000000, v244
	v_rsq_f32_e32 v3, v3
	v_add_u32_e32 v18, 19, v2
	v_ashrrev_i32_e32 v19, 31, v18
	v_lshlrev_b64 v[18:19], 11, v[18:19]
	v_mul_f32_e32 v13, v13, v3
	v_mul_f32_e32 v12, v12, v3
	v_mul_f32_e32 v11, v11, v3
	v_mul_f32_e32 v3, v10, v3
	v_lshl_add_u64 v[18:19], s[2:3], 0, v[18:19]
	v_mul_f32_e32 v13, v13, v76
	v_mul_f32_e32 v3, v3, v79
	v_lshl_add_u64 v[18:19], v[18:19], 0, s[36:37]
	v_bfe_u32 v20, v13, 16, 1
	v_bfe_u32 v10, v3, 16, 1
	v_lshl_add_u64 v[18:19], v[18:19], 0, v[0:1]
	v_add3_u32 v13, v13, v20, s86
	v_mul_f32_e32 v12, v12, v77
	v_add3_u32 v3, v3, v10, s86
	global_store_short_d16_hi v[18:19], v13, off offset:1024
	v_bfe_u32 v13, v12, 16, 1
	global_store_short_d16_hi v[18:19], v3, off offset:1216
	v_fmamk_f32 v3, v61, 0x3c000000, v244
	v_add3_u32 v12, v12, v13, s86
	v_mul_f32_e32 v11, v11, v78
	v_rsq_f32_e32 v3, v3
	global_store_short_d16_hi v[18:19], v12, off offset:1088
	v_bfe_u32 v12, v11, 16, 1
	v_add3_u32 v11, v11, v12, s86
	v_add_u32_e32 v10, 24, v2
	global_store_short_d16_hi v[18:19], v11, off offset:1152
	v_ashrrev_i32_e32 v11, 31, v10
	v_lshlrev_b64 v[10:11], 11, v[10:11]
	v_mul_f32_e32 v12, v29, v3
	v_lshl_add_u64 v[10:11], s[2:3], 0, v[10:11]
	v_mul_f32_e32 v12, v12, v76
	v_lshl_add_u64 v[10:11], v[10:11], 0, s[36:37]
	v_bfe_u32 v13, v12, 16, 1
	v_lshl_add_u64 v[10:11], v[10:11], 0, v[0:1]
	v_add3_u32 v12, v12, v13, s86
	global_store_short_d16_hi v[10:11], v12, off offset:1024
	v_mul_f32_e32 v12, v14, v3
	v_mul_f32_e32 v12, v12, v77
	v_bfe_u32 v13, v12, 16, 1
	v_add3_u32 v12, v12, v13, s86
	global_store_short_d16_hi v[10:11], v12, off offset:1088
	v_mul_f32_e32 v12, v28, v3
	v_mul_f32_e32 v3, v6, v3
	v_mul_f32_e32 v3, v3, v79
	v_bfe_u32 v6, v3, 16, 1
	v_add3_u32 v3, v3, v6, s86
	v_mul_f32_e32 v12, v12, v78
	global_store_short_d16_hi v[10:11], v3, off offset:1216
	v_fmamk_f32 v3, v59, 0x3c000000, v244
	v_bfe_u32 v13, v12, 16, 1
	v_rsq_f32_e32 v3, v3
	v_add3_u32 v12, v12, v13, s86
	global_store_short_d16_hi v[10:11], v12, off offset:1152
	v_add_u32_e32 v10, 25, v2
	v_ashrrev_i32_e32 v11, 31, v10
	v_lshlrev_b64 v[10:11], 11, v[10:11]
	v_mul_f32_e32 v6, v43, v3
	v_lshl_add_u64 v[10:11], s[2:3], 0, v[10:11]
	v_mul_f32_e32 v6, v6, v76
	v_lshl_add_u64 v[10:11], v[10:11], 0, s[36:37]
	v_bfe_u32 v12, v6, 16, 1
	v_lshl_add_u64 v[10:11], v[10:11], 0, v[0:1]
	v_add3_u32 v6, v6, v12, s86
	global_store_short_d16_hi v[10:11], v6, off offset:1024
	v_mul_f32_e32 v6, v15, v3
	v_mul_f32_e32 v6, v6, v77
	v_bfe_u32 v12, v6, 16, 1
	v_add3_u32 v6, v6, v12, s86
	global_store_short_d16_hi v[10:11], v6, off offset:1088
	v_mul_f32_e32 v6, v30, v3
	v_mul_f32_e32 v6, v6, v78
	v_bfe_u32 v12, v6, 16, 1
	v_mul_f32_e32 v3, v7, v3
	v_add3_u32 v6, v6, v12, s86
	v_mul_f32_e32 v3, v3, v79
	global_store_short_d16_hi v[10:11], v6, off offset:1152
	v_bfe_u32 v6, v3, 16, 1
	v_add3_u32 v3, v3, v6, s86
	global_store_short_d16_hi v[10:11], v3, off offset:1216
	v_fmamk_f32 v3, v49, 0x3c000000, v244
	v_rsq_f32_e32 v3, v3
	v_add_u32_e32 v6, 26, v2
	v_ashrrev_i32_e32 v7, 31, v6
	v_lshlrev_b64 v[6:7], 11, v[6:7]
	v_mul_f32_e32 v10, v31, v3
	v_lshl_add_u64 v[6:7], s[2:3], 0, v[6:7]
	v_mul_f32_e32 v10, v10, v76
	v_lshl_add_u64 v[6:7], v[6:7], 0, s[36:37]
	v_bfe_u32 v11, v10, 16, 1
	v_mul_f32_e32 v8, v8, v3
	v_lshl_add_u64 v[6:7], v[6:7], 0, v[0:1]
	v_add3_u32 v10, v10, v11, s86
	v_mul_f32_e32 v8, v8, v77
	global_store_short_d16_hi v[6:7], v10, off offset:1024
	v_bfe_u32 v10, v8, 16, 1
	v_add3_u32 v8, v8, v10, s86
	global_store_short_d16_hi v[6:7], v8, off offset:1088
	v_mul_f32_e32 v8, v16, v3
	v_mul_f32_e32 v3, v4, v3
	v_mul_f32_e32 v3, v3, v79
	v_bfe_u32 v4, v3, 16, 1
	v_add3_u32 v3, v3, v4, s86
	global_store_short_d16_hi v[6:7], v3, off offset:1216
	v_fmamk_f32 v3, v44, 0x3c000000, v244
	v_add_u32_e32 v2, 27, v2
	v_rsq_f32_e32 v4, v3
	v_ashrrev_i32_e32 v3, 31, v2
	v_lshlrev_b64 v[2:3], 11, v[2:3]
	v_lshl_add_u64 v[2:3], s[2:3], 0, v[2:3]
	v_mul_f32_e32 v8, v8, v78
	v_lshl_add_u64 v[2:3], v[2:3], 0, s[36:37]
	v_bfe_u32 v10, v8, 16, 1
	v_lshl_add_u64 v[2:3], v[2:3], 0, v[0:1]
	v_mul_f32_e32 v0, v32, v4
	v_add3_u32 v8, v8, v10, s86
	v_mul_f32_e32 v0, v76, v0
	global_store_short_d16_hi v[6:7], v8, off offset:1152
	v_bfe_u32 v6, v0, 16, 1
	v_add3_u32 v0, v0, v6, s86
	global_store_short_d16_hi v[2:3], v0, off offset:1024
	v_mul_f32_e32 v0, v17, v4
	v_mul_f32_e32 v0, v77, v0
	v_bfe_u32 v6, v0, 16, 1
	v_add3_u32 v0, v0, v6, s86
	global_store_short_d16_hi v[2:3], v0, off offset:1088
	v_mul_f32_e32 v0, v9, v4
	v_mul_f32_e32 v0, v78, v0
	v_bfe_u32 v6, v0, 16, 1
	v_add3_u32 v0, v0, v6, s86
	global_store_short_d16_hi v[2:3], v0, off offset:1152
	v_mul_f32_e32 v0, v5, v4
	v_mul_f32_e32 v0, v79, v0
	v_bfe_u32 v4, v0, 16, 1
	v_add3_u32 v0, v0, v4, s86
	global_store_short_d16_hi v[2:3], v0, off offset:1216
	s_waitcnt lgkmcnt(0)
	s_barrier
